# speedup vs baseline: 1.0047x; 1.0047x over previous
.LBB0_106:
	s_cmpk_gt_i32 s23, 0x3fff
	v_mbcnt_lo_u32_b32 v186, -1, 0
	s_cbranch_scc1 .LBB0_109
	v_mbcnt_hi_u32_b32 v3, -1, v186
	v_and_b32_e32 v4, 64, v3
	v_add_u32_e32 v4, 64, v4
	v_xor_b32_e32 v5, 1, v3
	v_cmp_lt_i32_e32 vcc, v5, v4
	s_ashr_i32 s4, s24, 31
	s_ashr_i32 s5, s76, 31
	v_cndmask_b32_e32 v5, v3, v5, vcc
	v_lshlrev_b32_e32 v6, 2, v5
	v_xor_b32_e32 v5, 2, v3
	v_cmp_lt_i32_e32 vcc, v5, v4
	s_add_u32 s8, s24, s76
	s_addc_u32 s9, s4, s5
	v_cndmask_b32_e32 v5, v3, v5, vcc
	v_lshlrev_b32_e32 v7, 2, v5
	v_xor_b32_e32 v5, 4, v3
	v_cmp_lt_i32_e32 vcc, v5, v4
	s_lshl_b64 s[4:5], s[8:9], 11
	s_add_u32 s4, s14, s4
	v_cndmask_b32_e32 v5, v3, v5, vcc
	v_lshlrev_b32_e32 v8, 2, v5
	v_xor_b32_e32 v5, 8, v3
	v_cmp_lt_i32_e32 vcc, v5, v4
	s_addc_u32 s5, s15, s5
	s_ashr_i32 s35, s34, 31
	v_cndmask_b32_e32 v5, v3, v5, vcc
	v_lshlrev_b32_e32 v9, 2, v5
	v_xor_b32_e32 v5, 16, v3
	v_cmp_lt_i32_e32 vcc, v5, v4
	s_lshl_b64 s[8:9], s[8:9], 12
	v_mov_b32_e32 v12, 0x358637bd
	v_cndmask_b32_e32 v5, v3, v5, vcc
	v_lshlrev_b32_e32 v10, 2, v5
	v_xor_b32_e32 v5, 32, v3
	v_cmp_lt_i32_e32 vcc, v5, v4
	s_mov_b32 s10, 0x800000
	s_nop 0
	v_cndmask_b32_e32 v3, v3, v5, vcc
	v_lshlrev_b32_e32 v11, 2, v3
	v_mov_b32_e32 v3, 0
	v_lshl_add_u64 v[4:5], s[4:5], 0, v[2:3]
	s_mov_b64 s[4:5], 0x3800400
	v_lshl_add_u64 v[4:5], v[4:5], 0, s[4:5]
	s_lshl_b64 s[4:5], s[34:35], 11
	s_add_u32 s8, s52, s8
	v_lshlrev_b32_e32 v2, 4, v44
	s_addc_u32 s9, s53, s9
	v_lshl_add_u64 v[2:3], s[8:9], 0, v[2:3]
	s_mov_b64 s[8:9], 0xc00
	v_lshl_add_u64 v[2:3], v[2:3], 0, s[8:9]
	s_lshl_b64 s[8:9], s[34:35], 12
	global_load_dwordx4 v[14:17], v[2:3], off offset:-3072
	global_load_dwordx4 v[18:21], v[2:3], off offset:-2048
	global_load_dwordx4 v[22:25], v[2:3], off offset:-1024
	global_load_dwordx4 v[26:29], v[2:3], off
	v_lshl_add_u64 v[2:3], v[2:3], 0, s[8:9]
	s_waitcnt vmcnt(0)
	s_mov_b32 s92, 0x55555555
	s_mov_b32 s93, 0x55555555

.Lxn_nopf:
	v_pk_mul_f32 v[30:31], v[16:17], v[16:17]
	v_pk_mul_f32 v[32:33], v[14:15], v[14:15]
	v_pk_mul_f32 v[34:35], v[20:21], v[20:21]
	v_pk_mul_f32 v[36:37], v[18:19], v[18:19]
	v_pk_mov_b32 v[44:45], v[32:33], v[30:31] op_sel:[1,0]
	v_mov_b32_e32 v33, v31
	v_pk_mov_b32 v[30:31], v[36:37], v[34:35] op_sel:[1,0]
	v_mov_b32_e32 v37, v35
	v_mul_f32_e32 v41, v27, v27
	v_mul_f32_e32 v38, v23, v23
	v_mul_f32_e32 v40, v25, v25
	v_pk_add_f32 v[32:33], v[44:45], v[32:33]
	v_pk_add_f32 v[30:31], v[30:31], v[36:37]
	v_mul_f32_e32 v13, v26, v26
	v_mul_f32_e32 v46, v28, v28
	v_mul_f32_e32 v47, v29, v29
	v_pk_fma_f32 v[34:35], v[22:23], v[22:23], v[38:39] op_sel_hi:[1,1,0]
	v_pk_fma_f32 v[38:39], v[24:25], v[24:25], v[40:41] op_sel_hi:[1,1,0]
	v_pk_add_f32 v[32:33], v[32:33], v[32:33] op_sel:[0,1] op_sel_hi:[1,0]
	v_pk_add_f32 v[30:31], v[30:31], v[30:31] op_sel:[0,1] op_sel_hi:[1,0]
	v_mov_b32_e32 v35, v46
	v_mov_b32_e32 v39, v47
	v_mov_b32_e32 v33, v13
	v_mov_b32_e32 v31, v41
	v_pk_add_f32 v[34:35], v[34:35], v[38:39]
	v_pk_add_f32 v[30:31], v[32:33], v[30:31]
	s_nop 0
	v_pk_add_f32 v[30:31], v[30:31], v[34:35]
	s_nop 0
	v_add_f32_e32 v13, v30, v31
	ds_bpermute_b32 v30, v6, v13
	s_waitcnt lgkmcnt(0)
	v_add_f32_e32 v13, v13, v30
	ds_bpermute_b32 v30, v7, v13
	s_waitcnt lgkmcnt(0)
	v_add_f32_e32 v13, v13, v30
	ds_bpermute_b32 v30, v8, v13
	s_waitcnt lgkmcnt(0)
	v_add_f32_e32 v13, v13, v30
	ds_bpermute_b32 v30, v9, v13
	s_waitcnt lgkmcnt(0)
	v_add_f32_e32 v13, v13, v30
	ds_bpermute_b32 v30, v10, v13
	s_waitcnt lgkmcnt(0)
	v_add_f32_e32 v13, v13, v30
	ds_bpermute_b32 v30, v11, v13
	s_waitcnt lgkmcnt(0)
	v_add_f32_e32 v13, v13, v30
	v_fmamk_f32 v13, v13, 0x3a800000, v12
	v_mul_f32_e32 v30, 0x4b800000, v13
	v_cmp_gt_f32_e32 vcc, s10, v13
	s_nop 1
	v_cndmask_b32_e32 v13, v13, v30, vcc
	v_rsq_f32_e32 v13, v13
	s_nop 0
	v_mul_f32_e32 v30, 0x45800000, v13
	v_cndmask_b32_e32 v30, v13, v30, vcc
	v_pk_mul_f32 v[14:15], v[30:31], v[14:15] op_sel_hi:[0,1]
	v_pk_mul_f32 v[16:17], v[30:31], v[16:17] op_sel_hi:[0,1]
	v_cvt_pk_bf16_f32 v14, v14, v15
	v_cvt_pk_bf16_f32 v15, v16, v17
	v_pk_mul_f32 v[20:21], v[30:31], v[20:21] op_sel_hi:[0,1]
	v_pk_mul_f32 v[18:19], v[30:31], v[18:19] op_sel_hi:[0,1]
	s_nop 1
	v_mov_b32_dpp v66, v14 quad_perm:[1,0,3,2] row_mask:0xf bank_mask:0xf
	v_mov_b32_dpp v67, v15 quad_perm:[1,0,3,2] row_mask:0xf bank_mask:0xf
	v_mov_b32_e32 v64, v14
	v_mov_b32_e32 v65, v15
	s_mov_b64 s[94:95], exec
	s_mov_b64 exec, s[92:93]
	global_store_dwordx4 v[4:5], v[64:67], off offset:-1024 sc0 sc1
	s_mov_b64 exec, s[94:95]
	v_cvt_pk_bf16_f32 v14, v18, v19
	v_cvt_pk_bf16_f32 v15, v20, v21
	v_pk_mul_f32 v[24:25], v[30:31], v[24:25] op_sel_hi:[0,1]
	v_pk_mul_f32 v[22:23], v[30:31], v[22:23] op_sel_hi:[0,1]
	s_nop 1
	v_mov_b32_dpp v66, v14 quad_perm:[1,0,3,2] row_mask:0xf bank_mask:0xf
	v_mov_b32_dpp v67, v15 quad_perm:[1,0,3,2] row_mask:0xf bank_mask:0xf
	v_mov_b32_e32 v64, v14
	v_mov_b32_e32 v65, v15
	s_mov_b64 s[94:95], exec
	s_mov_b64 exec, s[92:93]
	global_store_dwordx4 v[4:5], v[64:67], off offset:-512 sc0 sc1
	s_mov_b64 exec, s[94:95]
	v_cvt_pk_bf16_f32 v14, v22, v23
	v_cvt_pk_bf16_f32 v15, v24, v25
	v_pk_mul_f32 v[28:29], v[30:31], v[28:29] op_sel_hi:[0,1]
	v_pk_mul_f32 v[26:27], v[30:31], v[26:27] op_sel_hi:[0,1]
	s_nop 1
	v_mov_b32_dpp v66, v14 quad_perm:[1,0,3,2] row_mask:0xf bank_mask:0xf
	v_mov_b32_dpp v67, v15 quad_perm:[1,0,3,2] row_mask:0xf bank_mask:0xf
	v_mov_b32_e32 v64, v14
	v_mov_b32_e32 v65, v15
	s_mov_b64 s[94:95], exec
	s_mov_b64 exec, s[92:93]
	global_store_dwordx4 v[4:5], v[64:67], off sc0 sc1
	s_mov_b64 exec, s[94:95]
	v_cvt_pk_bf16_f32 v14, v26, v27
	v_cvt_pk_bf16_f32 v15, v28, v29
	s_nop 1
	v_mov_b32_dpp v66, v14 quad_perm:[1,0,3,2] row_mask:0xf bank_mask:0xf
	v_mov_b32_dpp v67, v15 quad_perm:[1,0,3,2] row_mask:0xf bank_mask:0xf
	v_mov_b32_e32 v64, v14
	v_mov_b32_e32 v65, v15
	s_mov_b64 s[94:95], exec
	s_mov_b64 exec, s[92:93]
	global_store_dwordx4 v[4:5], v[64:67], off offset:512 sc0 sc1
	s_mov_b64 exec, s[94:95]
	v_lshl_add_u64 v[4:5], v[4:5], 0, s[4:5]
	s_cbranch_scc1 .LBB0_109
	s_waitcnt vmcnt(4)
	v_mov_b64_e32 v[14:15], v[48:49]
	v_mov_b64_e32 v[16:17], v[50:51]
	v_mov_b64_e32 v[18:19], v[52:53]
	v_mov_b64_e32 v[20:21], v[54:55]
	v_mov_b64_e32 v[22:23], v[56:57]
	v_mov_b64_e32 v[24:25], v[58:59]
	v_mov_b64_e32 v[26:27], v[60:61]
	v_mov_b64_e32 v[28:29], v[62:63]
	s_branch .LBB0_108
